# dilated units: drop the 90 canonicalising v_max copies in the row-max trees (scores are MFMA results, never signalling NaNs)
# speedup vs baseline: 1.0038x; 1.0022x over previous
.LBB0_506:
	v_sub_u32_e32 v228, v184, v169
	v_subrev_u32_e32 v208, s92, v228
	v_cvt_f32_i32_e32 v16, v208
	s_andn2_b64 vcc, exec, s[96:97]
	v_add_f32_e32 v14, -1.0, v16
	v_pk_add_f32 v[0:1], v[16:17], s[12:13] op_sel_hi:[0,1]
	v_pk_add_f32 v[2:3], v[16:17], s[24:25] op_sel_hi:[0,1]
	v_pk_add_f32 v[4:5], v[16:17], s[28:29] op_sel_hi:[0,1]
	v_pk_add_f32 v[6:7], v[16:17], s[30:31] op_sel_hi:[0,1]
	v_pk_add_f32 v[8:9], v[16:17], s[36:37] op_sel_hi:[0,1]
	v_pk_add_f32 v[10:11], v[16:17], s[38:39] op_sel_hi:[0,1]
	v_pk_add_f32 v[12:13], v[16:17], s[40:41] op_sel_hi:[0,1]
	v_and_b32_e32 v1, 0x7fffffff, v1
	v_and_b32_e32 v0, 0x7fffffff, v0
	v_and_b32_e32 v3, 0x7fffffff, v3
	v_and_b32_e32 v2, 0x7fffffff, v2
	v_and_b32_e32 v5, 0x7fffffff, v5
	v_and_b32_e32 v4, 0x7fffffff, v4
	v_and_b32_e32 v7, 0x7fffffff, v7
	v_and_b32_e32 v6, 0x7fffffff, v6
	v_and_b32_e32 v9, 0x7fffffff, v9
	v_and_b32_e32 v8, 0x7fffffff, v8
	v_and_b32_e32 v11, 0x7fffffff, v11
	v_and_b32_e32 v10, 0x7fffffff, v10
	v_and_b32_e32 v13, 0x7fffffff, v13
	v_and_b32_e32 v12, 0x7fffffff, v12
	v_and_b32_e32 v18, 0x7fffffff, v16
	v_and_b32_e32 v19, 0x7fffffff, v14
	v_pk_mul_f32 v[14:15], v[12:13], v[186:187] op_sel_hi:[1,0] neg_lo:[0,1] neg_hi:[0,1]
	v_pk_mul_f32 v[12:13], v[10:11], v[186:187] op_sel_hi:[1,0] neg_lo:[0,1] neg_hi:[0,1]
	v_pk_mul_f32 v[10:11], v[8:9], v[186:187] op_sel_hi:[1,0] neg_lo:[0,1] neg_hi:[0,1]
	v_pk_mul_f32 v[8:9], v[6:7], v[186:187] op_sel_hi:[1,0] neg_lo:[0,1] neg_hi:[0,1]
	v_pk_mul_f32 v[6:7], v[4:5], v[186:187] op_sel_hi:[1,0] neg_lo:[0,1] neg_hi:[0,1]
	v_pk_mul_f32 v[4:5], v[2:3], v[186:187] op_sel_hi:[1,0] neg_lo:[0,1] neg_hi:[0,1]
	v_pk_mul_f32 v[2:3], v[0:1], v[186:187] op_sel_hi:[1,0] neg_lo:[0,1] neg_hi:[0,1]
	v_pk_mul_f32 v[0:1], v[18:19], v[186:187] op_sel_hi:[1,0] neg_lo:[0,1] neg_hi:[0,1]
	v_pk_add_f32 v[18:19], v[16:17], s[64:65] op_sel_hi:[0,1]
	v_pk_add_f32 v[20:21], v[16:17], s[66:67] op_sel_hi:[0,1]
	v_pk_add_f32 v[22:23], v[16:17], s[68:69] op_sel_hi:[0,1]
	v_pk_add_f32 v[26:27], v[16:17], s[72:73] op_sel_hi:[0,1]
	v_pk_add_f32 v[28:29], v[16:17], s[74:75] op_sel_hi:[0,1]
	v_pk_add_f32 v[30:31], v[16:17], s[76:77] op_sel_hi:[0,1]
	v_and_b32_e32 v145, 0x7fffffff, v31
	v_and_b32_e32 v144, 0x7fffffff, v30
	v_and_b32_e32 v147, 0x7fffffff, v29
	v_and_b32_e32 v146, 0x7fffffff, v28
	v_and_b32_e32 v149, 0x7fffffff, v27
	v_and_b32_e32 v148, 0x7fffffff, v26
	v_and_b32_e32 v23, 0x7fffffff, v23
	v_and_b32_e32 v22, 0x7fffffff, v22
	v_and_b32_e32 v21, 0x7fffffff, v21
	v_and_b32_e32 v20, 0x7fffffff, v20
	v_and_b32_e32 v19, 0x7fffffff, v19
	v_and_b32_e32 v18, 0x7fffffff, v18
	v_pk_mul_f32 v[30:31], v[18:19], v[186:187] op_sel_hi:[1,0] neg_lo:[0,1] neg_hi:[0,1]
	v_pk_mul_f32 v[28:29], v[20:21], v[186:187] op_sel_hi:[1,0] neg_lo:[0,1] neg_hi:[0,1]
	v_pk_mul_f32 v[26:27], v[22:23], v[186:187] op_sel_hi:[1,0] neg_lo:[0,1] neg_hi:[0,1]
	v_pk_mul_f32 v[22:23], v[148:149], v[186:187] op_sel_hi:[1,0] neg_lo:[0,1] neg_hi:[0,1]
	v_pk_mul_f32 v[20:21], v[146:147], v[186:187] op_sel_hi:[1,0] neg_lo:[0,1] neg_hi:[0,1]
	v_pk_mul_f32 v[18:19], v[144:145], v[186:187] op_sel_hi:[1,0] neg_lo:[0,1] neg_hi:[0,1]
	ds_read_b128 v[144:147], v223
	ds_read_b128 v[148:151], v223 offset:4096
	v_pk_add_f32 v[24:25], v[16:17], s[70:71] op_sel_hi:[0,1]
	v_pk_add_f32 v[16:17], v[16:17], s[78:79] op_sel_hi:[0,1]
	v_and_b32_e32 v17, 0x7fffffff, v17
	v_and_b32_e32 v16, 0x7fffffff, v16
	v_and_b32_e32 v25, 0x7fffffff, v25
	v_and_b32_e32 v24, 0x7fffffff, v24
	v_pk_mul_f32 v[24:25], v[24:25], v[186:187] op_sel_hi:[1,0] neg_lo:[0,1] neg_hi:[0,1]
	v_pk_mul_f32 v[16:17], v[16:17], v[186:187] op_sel_hi:[1,0] neg_lo:[0,1] neg_hi:[0,1]
	s_waitcnt vmcnt(3) lgkmcnt(1)
	v_mfma_f32_32x32x16_bf16 v[0:15], v[144:147], v[136:139], v[0:15]
	s_waitcnt lgkmcnt(0)
	v_mfma_f32_32x32x16_bf16 v[16:31], v[148:151], v[136:139], v[16:31]
	ds_read_b128 v[144:147], v224
	ds_read_b128 v[148:151], v224 offset:4096
	s_waitcnt vmcnt(2) lgkmcnt(1)
	v_mfma_f32_32x32x16_bf16 v[0:15], v[144:147], v[132:135], v[0:15]
	s_waitcnt lgkmcnt(0)
	v_mfma_f32_32x32x16_bf16 v[16:31], v[148:151], v[132:135], v[16:31]
	ds_read_b128 v[144:147], v225
	ds_read_b128 v[148:151], v225 offset:4096
	s_waitcnt vmcnt(1) lgkmcnt(1)
	v_mfma_f32_32x32x16_bf16 v[0:15], v[144:147], v[128:131], v[0:15]
	s_waitcnt lgkmcnt(0)
	v_mfma_f32_32x32x16_bf16 v[16:31], v[148:151], v[128:131], v[16:31]
	ds_read_b128 v[144:147], v226
	ds_read_b128 v[148:151], v226 offset:4096
	s_waitcnt vmcnt(0) lgkmcnt(1)
	v_mfma_f32_32x32x16_bf16 v[0:15], v[144:147], v[124:127], v[0:15]
	s_waitcnt lgkmcnt(0)
	v_mfma_f32_32x32x16_bf16 v[16:31], v[148:151], v[124:127], v[16:31]
	s_nop 9
	v_max_f32_e32 v144, v1, v17
	v_max_f32_e32 v145, v2, v18
	v_max3_f32 v144, v0, v16, v144
	v_max_f32_e32 v146, v3, v19
	v_max3_f32 v144, v144, v145, v146
	v_max_f32_e32 v145, v4, v20
	v_max_f32_e32 v146, v5, v21
	v_max3_f32 v144, v144, v145, v146
	v_max_f32_e32 v145, v6, v22
	v_max_f32_e32 v146, v7, v23
	v_max3_f32 v144, v144, v145, v146
	v_max_f32_e32 v145, v8, v24
	v_max_f32_e32 v146, v9, v25
	v_max3_f32 v144, v144, v145, v146
	v_max_f32_e32 v145, v10, v26
	v_max_f32_e32 v146, v11, v27
	v_max3_f32 v144, v144, v145, v146
	v_max_f32_e32 v145, v12, v28
	v_max_f32_e32 v146, v13, v29
	v_max3_f32 v144, v144, v145, v146
	v_max_f32_e32 v145, v14, v30
	v_max_f32_e32 v146, v15, v31
	v_max3_f32 v144, v144, v145, v146
	v_mov_b32_e32 v145, v144
	s_nop 1
	v_permlane32_swap_b32 v144, v145
	s_nop 1
	ds_read_b128 v[234:237], v224 offset:8192
	v_max_f32_e32 v145, v145, v145
	v_max_f32_e32 v144, v144, v144
	v_max_f32_e32 v188, v144, v145
	v_sub_f32_e32 v0, v0, v188
	v_sub_f32_e32 v16, v16, v188
	v_sub_f32_e32 v1, v1, v188
	v_sub_f32_e32 v17, v17, v188
	v_exp_f32_e32 v184, v0
	v_exp_f32_e32 v185, v16
	v_sub_f32_e32 v2, v2, v188
	v_sub_f32_e32 v18, v18, v188
	v_exp_f32_e32 v190, v1
	v_exp_f32_e32 v191, v17
	v_sub_f32_e32 v3, v3, v188
	v_sub_f32_e32 v19, v19, v188
	v_exp_f32_e32 v192, v2
	v_exp_f32_e32 v193, v18
	v_sub_f32_e32 v4, v4, v188
	v_sub_f32_e32 v20, v20, v188
	v_exp_f32_e32 v194, v3
	v_exp_f32_e32 v195, v19
	v_sub_f32_e32 v5, v5, v188
	v_sub_f32_e32 v21, v21, v188
	v_pk_add_f32 v[0:1], v[184:185], 0 op_sel_hi:[1,0]
	v_exp_f32_e32 v196, v4
	v_exp_f32_e32 v197, v20
	v_sub_f32_e32 v6, v6, v188
	v_sub_f32_e32 v22, v22, v188
	v_pk_add_f32 v[0:1], v[190:191], v[0:1]
	v_exp_f32_e32 v198, v5
	v_exp_f32_e32 v199, v21
	v_sub_f32_e32 v7, v7, v188
	v_sub_f32_e32 v23, v23, v188
	v_pk_add_f32 v[0:1], v[192:193], v[0:1]
	v_exp_f32_e32 v204, v6
	v_exp_f32_e32 v205, v22
	v_sub_f32_e32 v8, v8, v188
	v_sub_f32_e32 v24, v24, v188
	v_pk_add_f32 v[0:1], v[194:195], v[0:1]
	v_exp_f32_e32 v206, v7
	v_exp_f32_e32 v207, v23
	v_sub_f32_e32 v9, v9, v188
	v_sub_f32_e32 v25, v25, v188
	v_exp_f32_e32 v144, v8
	v_exp_f32_e32 v145, v24
	v_pk_add_f32 v[0:1], v[196:197], v[0:1]
	v_sub_f32_e32 v10, v10, v188
	v_sub_f32_e32 v26, v26, v188
	v_exp_f32_e32 v146, v9
	v_exp_f32_e32 v147, v25
	v_pk_add_f32 v[0:1], v[198:199], v[0:1]
	v_sub_f32_e32 v11, v11, v188
	v_sub_f32_e32 v27, v27, v188
	v_exp_f32_e32 v148, v10
	v_exp_f32_e32 v149, v26
	v_pk_add_f32 v[0:1], v[204:205], v[0:1]
	v_sub_f32_e32 v12, v12, v188
	v_sub_f32_e32 v28, v28, v188
	v_exp_f32_e32 v150, v11
	v_exp_f32_e32 v151, v27
	v_pk_add_f32 v[0:1], v[206:207], v[0:1]
	v_sub_f32_e32 v13, v13, v188
	v_sub_f32_e32 v29, v29, v188
	v_exp_f32_e32 v152, v12
	v_exp_f32_e32 v153, v28
	v_pk_add_f32 v[0:1], v[144:145], v[0:1]
	v_sub_f32_e32 v14, v14, v188
	v_sub_f32_e32 v30, v30, v188
	v_exp_f32_e32 v154, v13
	v_exp_f32_e32 v155, v29
	v_pk_add_f32 v[0:1], v[146:147], v[0:1]
	ds_read_b128 v[4:7], v223 offset:8192
	v_sub_f32_e32 v15, v15, v188
	v_sub_f32_e32 v31, v31, v188
	v_exp_f32_e32 v156, v14
	v_exp_f32_e32 v157, v30
	v_pk_add_f32 v[0:1], v[148:149], v[0:1]
	v_exp_f32_e32 v158, v15
	v_exp_f32_e32 v159, v31
	v_pk_add_f32 v[0:1], v[150:151], v[0:1]
	v_cvt_pk_bf16_f32 v2, v196, v198
	v_pk_add_f32 v[0:1], v[152:153], v[0:1]
	v_cvt_pk_bf16_f32 v3, v204, v206
	v_pk_add_f32 v[0:1], v[154:155], v[0:1]
	v_cvt_pk_bf16_f32 v230, v144, v146
	v_pk_add_f32 v[0:1], v[156:157], v[0:1]
	v_cvt_pk_bf16_f32 v231, v148, v150
	v_pk_add_f32 v[0:1], v[158:159], v[0:1]
	v_cvt_pk_bf16_f32 v232, v152, v154
	v_pk_add_f32 v[0:1], v[0:1], v[0:1] op_sel_hi:[0,1]
	v_mov_b32_e32 v189, v1
	v_cvt_pk_bf16_f32 v0, v184, v190
	v_cvt_pk_bf16_f32 v1, v192, v194
	v_cvt_pk_bf16_f32 v233, v156, v158
	v_cvt_pk_bf16_f32 v190, v185, v191
	s_waitcnt lgkmcnt(0)
	v_mfma_f32_32x32x16_bf16 v[16:31], v[4:7], v[0:3], 0
	ds_read_b128 v[4:7], v223 offset:12288
	v_cvt_pk_bf16_f32 v191, v193, v195
	v_cvt_pk_bf16_f32 v192, v197, v199
	ds_read_b128 v[194:197], v225 offset:8192
	v_cvt_pk_bf16_f32 v193, v205, v207
	v_cvt_pk_bf16_f32 v144, v145, v147
	v_cvt_pk_bf16_f32 v145, v149, v151
	v_mfma_f32_32x32x16_bf16 v[16:31], v[234:237], v[230:233], v[16:31]
	ds_read_b128 v[234:237], v224 offset:12288
	ds_read_b128 v[148:151], v226 offset:8192
	v_cvt_pk_bf16_f32 v146, v153, v155
	v_cvt_pk_bf16_f32 v147, v157, v159
	v_add_f32_e64 v188, v188, 0
	v_add_f32_e64 v189, v189, 0
	s_waitcnt lgkmcnt(3)
	v_mfma_f32_32x32x16_bf16 v[0:15], v[4:7], v[0:3], 0
	s_waitcnt lgkmcnt(2)
	v_mfma_f32_32x32x16_bf16 v[16:31], v[194:197], v[190:193], v[16:31]
	ds_read_b128 v[194:197], v225 offset:12288
	s_waitcnt lgkmcnt(2)
	v_mfma_f32_32x32x16_bf16 v[0:15], v[234:237], v[230:233], v[0:15]
	s_waitcnt lgkmcnt(1)
	v_mfma_f32_32x32x16_bf16 v[16:31], v[148:151], v[144:147], v[16:31]
	ds_read_b128 v[148:151], v226 offset:12288
	s_waitcnt lgkmcnt(1)
	v_mfma_f32_32x32x16_bf16 v[0:15], v[194:197], v[190:193], v[0:15]
	s_waitcnt lgkmcnt(0)
	v_mfma_f32_32x32x16_bf16 v[0:15], v[148:151], v[144:147], v[0:15]
	s_cbranch_vccnz .LBB0_511
	s_and_b64 vcc, exec, s[90:91]
	ds_write_b128 v222, v[64:67]
	ds_write_b128 v222, v[68:71] offset:8192
	ds_write_b128 v222, v[72:75] offset:1024
	ds_write_b128 v222, v[76:79] offset:9216
	ds_write_b128 v222, v[80:83] offset:2048
	ds_write_b128 v222, v[84:87] offset:10240
	ds_write_b128 v222, v[88:91] offset:3072
	ds_write_b128 v222, v[92:95] offset:11264
	ds_write_b128 v222, v[96:99] offset:4096
	ds_write_b128 v222, v[100:103] offset:12288
	ds_write_b128 v222, v[104:107] offset:5120
	ds_write_b128 v222, v[108:111] offset:13312
	ds_write_b128 v222, v[112:115] offset:6144
	ds_write_b128 v222, v[116:119] offset:14336
	ds_write_b128 v222, v[120:123] offset:7168
	ds_write_b128 v222, v[140:143] offset:15360
	s_cbranch_vccz .LBB0_512
	v_mov_b64_e32 v[158:159], v[34:35]
	v_mov_b64_e32 v[154:155], v[38:39]
	v_mov_b64_e32 v[150:151], v[42:43]
	v_mov_b64_e32 v[146:147], v[46:47]
	s_andn2_b64 vcc, exec, s[86:87]
	v_mov_b64_e32 v[192:193], v[60:61]
	v_mov_b64_e32 v[194:195], v[62:63]
	v_mov_b64_e32 v[196:197], v[200:201]
	v_mov_b64_e32 v[198:199], v[202:203]
	v_mov_b64_e32 v[190:191], v[56:57]
	v_mov_b32_e32 v177, v59
	s_mov_b32 s90, s94
	s_mov_b32 s95, s15
	s_mov_b32 s34, s48
	v_mov_b32_e32 v184, v58
	s_mov_b32 s93, s35
	s_mov_b32 s56, s33
	v_mov_b64_e32 v[156:157], v[32:33]
	v_mov_b64_e32 v[152:153], v[36:37]
	v_mov_b64_e32 v[148:149], v[40:41]
	v_mov_b64_e32 v[144:145], v[44:45]
	s_cbranch_vccnz .LBB0_510
	s_add_i32 s8, s14, s63
	s_lshr_b32 s56, s8, 8
	s_mul_hi_u32 s85, s56, 0x55555556
	s_mul_i32 s85, s85, 3
	s_sub_i32 s93, s56, s85
	s_lshl_b32 s95, s93, 1
	s_lshr_b32 s90, 0x100, s95
	s_and_b32 s34, s8, 0xff
	s_sub_i32 s85, 8, s95
	s_add_i32 s90, s90, -1
	s_mul_hi_u32 s8, s8, 0xaaaaaaab
	s_lshr_b32 s85, s34, s85
	s_and_b32 s34, s90, s34
	s_bfe_u32 s56, s8, 0x30009
	s_lshl_b32 s34, s34, 5
	s_lshl_b32 s8, s8, 1
	s_and_b32 s91, s8, 0xfe000
	v_or_b32_e32 v184, s34, v162
	v_mov_b32_e32 v185, v167
	v_lshlrev_b64 v[64:65], s95, v[184:185]
	s_or_b32 s8, s85, s91
	s_add_i32 s96, s56, 1
	v_lshl_add_u64 v[190:191], v[64:65], 0, s[8:9]
	v_cvt_f32_ubyte0_e32 v64, s96
	v_exp_f32_e64 v185, -v64
	s_lshl_b32 s96, 1, s95
	v_lshlrev_b64 v[64:65], 12, v[190:191]
	v_cvt_f32_u32_e32 v204, s96
	v_lshl_add_u64 v[64:65], s[22:23], 0, v[64:65]
	s_lshl_b32 s96, s56, 7
	s_mov_b32 s97, s9
	v_lshl_add_u64 v[64:65], v[64:65], 0, s[96:97]
	v_mov_b32_e32 v177, v167
	v_lshl_add_u64 v[156:157], v[64:65], 0, v[176:177]
	v_lshlrev_b32_e32 v64, s95, v168
	v_add_u32_e32 v64, s8, v64
	v_mov_b32_e32 v65, v167
	s_and_b32 s90, s34, 0x1fc0
	v_lshlrev_b64 v[64:65], 12, v[64:65]
	v_lshl_add_u64 v[64:65], s[22:23], 0, v[64:65]
	s_cmp_eq_u32 s93, 1
	v_lshl_add_u64 v[64:65], v[64:65], 0, s[96:97]
	s_cselect_b32 s8, s20, s26
	s_cselect_b32 s96, s21, s27
	s_cmp_eq_u32 s93, 0
	s_cselect_b32 s96, s54, s96
	s_cselect_b32 s8, s49, s8
	v_lshl_or_b32 v66, s56, 6, v164
	v_lshl_add_u64 v[112:113], v[64:65], 0, v[178:179]
	v_lshl_add_u64 v[120:121], v[64:65], 0, v[180:181]
	v_mov_b32_e32 v64, s8
	v_mov_b32_e32 v65, s96
	v_mul_i32_i24_e32 v66, 0x18000, v66
	v_mov_b32_e32 v67, v167
	v_lshl_add_u64 v[64:65], v[66:67], 1, v[64:65]
	s_lshl_b32 s8, s91, 1
	v_lshl_add_u64 v[64:65], v[64:65], 0, s[8:9]
	s_sub_i32 s8, 13, s95
	s_lshl_b32 s8, s85, s8
	s_mov_b32 s91, s9
	s_lshl_b32 s8, s8, 1
	s_lshl_b64 s[96:97], s[90:91], s95
	v_lshl_add_u64 v[64:65], v[64:65], 0, s[8:9]
	s_lshl_b64 s[96:97], s[96:97], 12
	v_lshl_add_u64 v[196:197], v[64:65], 0, v[178:179]
	v_lshl_add_u64 v[198:199], v[64:65], 0, v[180:181]
	v_lshl_add_u64 v[64:65], v[112:113], 0, s[96:97]
	s_lshl_b32 s8, s90, 1
	s_or_b32 s96, s90, 4
	s_mov_b32 s97, s9
	s_lshl_b64 s[96:97], s[96:97], s95
	v_lshl_add_u64 v[140:141], v[198:199], 0, s[8:9]
	v_lshl_add_u64 v[116:117], v[196:197], 0, s[8:9]
	s_lshl_b64 s[96:97], s[96:97], 12
	v_add_co_u32_e32 v76, vcc, s1, v140
	s_or_b32 s8, s90, 16
	v_lshl_add_u64 v[72:73], v[120:121], 0, s[96:97]
	v_addc_co_u32_e32 v77, vcc, 0, v141, vcc
	s_lshl_b64 s[96:97], s[8:9], s95
	s_lshl_b64 s[96:97], s[96:97], 12
	v_add_co_u32_e32 v84, vcc, s52, v116
	s_or_b32 s8, s90, 20
	v_lshl_add_u64 v[80:81], v[112:113], 0, s[96:97]
	v_addc_co_u32_e32 v85, vcc, 0, v117, vcc
	s_lshl_b64 s[96:97], s[8:9], s95
	s_lshl_b64 s[96:97], s[96:97], 12
	v_add_co_u32_e32 v92, vcc, s53, v140
	s_or_b32 s8, s34, 32
	v_lshl_add_u64 v[88:89], v[120:121], 0, s[96:97]
	v_addc_co_u32_e32 v93, vcc, 0, v141, vcc
	s_lshl_b64 s[96:97], s[8:9], s95
	s_lshl_b64 s[96:97], s[96:97], 12
	v_add_co_u32_e32 v100, vcc, s6, v116
	s_or_b32 s8, s34, 36
	v_lshl_add_u64 v[96:97], v[112:113], 0, s[96:97]
	v_addc_co_u32_e32 v101, vcc, 0, v117, vcc
	s_lshl_b64 s[96:97], s[8:9], s95
	s_lshl_b64 s[96:97], s[96:97], 12
	v_add_co_u32_e32 v108, vcc, s7, v140
	s_or_b32 s8, s34, 48
	v_lshl_add_u64 v[104:105], v[120:121], 0, s[96:97]
	v_addc_co_u32_e32 v109, vcc, 0, v141, vcc
	s_lshl_b64 s[96:97], s[8:9], s95
	global_load_dwordx4 v[68:71], v[116:117], off
	s_lshl_b64 s[96:97], s[96:97], 12
	v_add_co_u32_e32 v116, vcc, s42, v116
	s_or_b32 s8, s34, 52
	v_lshl_add_u64 v[192:193], v[112:113], 0, s[10:11]
	v_lshl_add_u64 v[112:113], v[112:113], 0, s[96:97]
	v_addc_co_u32_e32 v117, vcc, 0, v117, vcc
	s_lshl_b64 s[96:97], s[8:9], s95
	s_lshl_b64 s[96:97], s[96:97], 12
	v_add_co_u32_e32 v140, vcc, 0xa80000, v140
	v_lshl_add_u64 v[194:195], v[120:121], 0, s[10:11]
	v_lshl_add_u64 v[120:121], v[120:121], 0, s[96:97]
	v_addc_co_u32_e32 v141, vcc, 0, v141, vcc
	global_load_dwordx4 v[64:67], v[64:65], off offset:3072
	v_mul_f32_e32 v177, 0x3fb8aa3b, v185
	global_load_dwordx4 v[72:75], v[72:73], off offset:3072
	s_lshr_b32 s34, 0x2000, s95
	global_load_dwordx4 v[76:79], v[76:77], off
	v_mul_f32_e32 v177, v177, v204
	global_load_dwordx4 v[80:83], v[80:81], off offset:3072
	s_nop 0
	global_load_dwordx4 v[84:87], v[84:85], off
	s_nop 0
	global_load_dwordx4 v[88:91], v[88:89], off offset:3072
	s_nop 0
	global_load_dwordx4 v[92:95], v[92:93], off
	s_nop 0
	global_load_dwordx4 v[96:99], v[96:97], off offset:3072
	s_nop 0
	global_load_dwordx4 v[100:103], v[100:101], off
	s_nop 0
	global_load_dwordx4 v[104:107], v[104:105], off offset:3072
	s_nop 0
	global_load_dwordx4 v[108:111], v[108:109], off
	s_nop 0
	global_load_dwordx4 v[112:115], v[112:113], off offset:3072
	s_nop 0
	global_load_dwordx4 v[116:119], v[116:117], off
	s_nop 0
	global_load_dwordx4 v[120:123], v[120:121], off offset:3072
	s_nop 0
	global_load_dwordx4 v[140:143], v[140:141], off
	s_nop 0
	global_load_dwordx4 v[144:147], v[156:157], off offset:2048
	global_load_dwordx4 v[148:151], v[156:157], off offset:2080
	global_load_dwordx4 v[152:155], v[156:157], off offset:2112
	s_nop 0
	global_load_dwordx4 v[156:159], v[156:157], off offset:2144

.LBB0_514:
	v_add_u32_e32 v32, 64, v208
	v_cvt_f32_i32_e32 v63, v32
	ds_read_b128 v[200:203], v223
	ds_read_b128 v[204:207], v223 offset:4096
	v_add_f32_e32 v33, 0xc2000000, v63
	v_fma_f32 v32, -v186, |v63|, -v188
	v_cmp_ngt_f32_e64 vcc, |v63|, s50
	v_fma_f32 v34, -v186, |v33|, -v188
	v_add_f32_e32 v62, 0xc2580000, v63
	v_cndmask_b32_e32 v32, v227, v32, vcc
	v_cmp_ngt_f32_e64 vcc, |v33|, s50
	v_add_f32_e32 v33, -1.0, v63
	v_fma_f32 v35, -v186, |v33|, -v188
	v_cndmask_b32_e32 v48, v227, v34, vcc
	v_add_f32_e32 v34, 0xc2040000, v63
	v_cmp_ngt_f32_e64 vcc, |v33|, s50
	v_fma_f32 v36, -v186, |v34|, -v188
	s_nop 0
	v_cndmask_b32_e32 v33, v227, v35, vcc
	v_cmp_ngt_f32_e64 vcc, |v34|, s50
	v_add_f32_e32 v34, -2.0, v63
	v_add_f32_e32 v35, 0xc2080000, v63
	v_cndmask_b32_e32 v49, v227, v36, vcc
	v_fma_f32 v36, -v186, |v34|, -v188
	v_cmp_ngt_f32_e64 vcc, |v34|, s50
	v_fma_f32 v37, -v186, |v35|, -v188
	s_nop 0
	v_cndmask_b32_e32 v34, v227, v36, vcc
	v_cmp_ngt_f32_e64 vcc, |v35|, s50
	v_add_f32_e32 v35, 0xc0400000, v63
	v_add_f32_e32 v36, 0xc20c0000, v63
	v_cndmask_b32_e32 v50, v227, v37, vcc
	v_fma_f32 v37, -v186, |v35|, -v188
	v_cmp_ngt_f32_e64 vcc, |v35|, s50
	v_fma_f32 v38, -v186, |v36|, -v188
	s_nop 0
	v_cndmask_b32_e32 v35, v227, v37, vcc
	v_cmp_ngt_f32_e64 vcc, |v36|, s50
	v_add_f32_e32 v36, -4.0, v63
	v_add_f32_e32 v37, 0xc2100000, v63
	v_cndmask_b32_e32 v51, v227, v38, vcc
	v_fma_f32 v38, -v186, |v36|, -v188
	v_cmp_ngt_f32_e64 vcc, |v36|, s50
	v_fma_f32 v39, -v186, |v37|, -v188
	s_nop 0
	v_cndmask_b32_e32 v36, v227, v38, vcc
	v_cmp_ngt_f32_e64 vcc, |v37|, s50
	v_add_f32_e32 v37, 0xc0a00000, v63
	v_add_f32_e32 v38, 0xc2140000, v63
	v_cndmask_b32_e32 v52, v227, v39, vcc
	v_fma_f32 v39, -v186, |v37|, -v188
	v_cmp_ngt_f32_e64 vcc, |v37|, s50
	v_fma_f32 v40, -v186, |v38|, -v188
	s_nop 0
	v_cndmask_b32_e32 v37, v227, v39, vcc
	v_cmp_ngt_f32_e64 vcc, |v38|, s50
	v_add_f32_e32 v38, 0xc0c00000, v63
	v_add_f32_e32 v39, 0xc2180000, v63
	v_cndmask_b32_e32 v53, v227, v40, vcc
	v_fma_f32 v40, -v186, |v38|, -v188
	v_cmp_ngt_f32_e64 vcc, |v38|, s50
	v_fma_f32 v41, -v186, |v39|, -v188
	s_nop 0
	v_cndmask_b32_e32 v38, v227, v40, vcc
	v_cmp_ngt_f32_e64 vcc, |v39|, s50
	v_add_f32_e32 v39, 0xc0e00000, v63
	v_add_f32_e32 v40, 0xc21c0000, v63
	v_cndmask_b32_e32 v54, v227, v41, vcc
	v_fma_f32 v41, -v186, |v39|, -v188
	v_cmp_ngt_f32_e64 vcc, |v39|, s50
	v_fma_f32 v42, -v186, |v40|, -v188
	s_nop 0
	v_cndmask_b32_e32 v39, v227, v41, vcc
	v_cmp_ngt_f32_e64 vcc, |v40|, s50
	v_add_f32_e32 v40, 0xc1800000, v63
	v_add_f32_e32 v41, 0xc2400000, v63
	v_cndmask_b32_e32 v55, v227, v42, vcc
	v_fma_f32 v42, -v186, |v40|, -v188
	v_cmp_ngt_f32_e64 vcc, |v40|, s50
	v_fma_f32 v43, -v186, |v41|, -v188
	s_nop 0
	v_cndmask_b32_e32 v40, v227, v42, vcc
	v_cmp_ngt_f32_e64 vcc, |v41|, s50
	v_add_f32_e32 v41, 0xc1880000, v63
	v_add_f32_e32 v42, 0xc2440000, v63
	v_cndmask_b32_e32 v56, v227, v43, vcc
	v_fma_f32 v43, -v186, |v41|, -v188
	v_cmp_ngt_f32_e64 vcc, |v41|, s50
	v_fma_f32 v44, -v186, |v42|, -v188
	s_nop 0
	v_cndmask_b32_e32 v41, v227, v43, vcc
	v_cmp_ngt_f32_e64 vcc, |v42|, s50
	v_add_f32_e32 v42, 0xc1900000, v63
	v_add_f32_e32 v43, 0xc2480000, v63
	v_cndmask_b32_e32 v57, v227, v44, vcc
	v_fma_f32 v44, -v186, |v42|, -v188
	v_cmp_ngt_f32_e64 vcc, |v42|, s50
	v_fma_f32 v45, -v186, |v43|, -v188
	s_nop 0
	v_cndmask_b32_e32 v42, v227, v44, vcc
	v_cmp_ngt_f32_e64 vcc, |v43|, s50
	v_add_f32_e32 v43, 0xc1980000, v63
	v_add_f32_e32 v44, 0xc24c0000, v63
	v_cndmask_b32_e32 v58, v227, v45, vcc
	v_fma_f32 v45, -v186, |v43|, -v188
	v_cmp_ngt_f32_e64 vcc, |v43|, s50
	v_fma_f32 v46, -v186, |v44|, -v188
	s_nop 0
	v_cndmask_b32_e32 v43, v227, v45, vcc
	v_cmp_ngt_f32_e64 vcc, |v44|, s50
	v_add_f32_e32 v44, 0xc1a00000, v63
	v_add_f32_e32 v45, 0xc2500000, v63
	v_cndmask_b32_e32 v59, v227, v46, vcc
	v_fma_f32 v46, -v186, |v44|, -v188
	v_cmp_ngt_f32_e64 vcc, |v44|, s50
	v_fma_f32 v47, -v186, |v45|, -v188
	s_nop 0
	v_cndmask_b32_e32 v44, v227, v46, vcc
	v_cmp_ngt_f32_e64 vcc, |v45|, s50
	v_add_f32_e32 v45, 0xc1a80000, v63
	v_add_f32_e32 v46, 0xc2540000, v63
	v_cndmask_b32_e32 v60, v227, v47, vcc
	v_fma_f32 v47, -v186, |v45|, -v188
	v_cmp_ngt_f32_e64 vcc, |v45|, s50
	v_fma_f32 v61, -v186, |v46|, -v188
	s_nop 0
	v_cndmask_b32_e32 v45, v227, v47, vcc
	v_cmp_ngt_f32_e64 vcc, |v46|, s50
	v_add_f32_e32 v46, 0xc1b00000, v63
	v_fma_f32 v47, -v186, |v46|, -v188
	v_cndmask_b32_e32 v61, v227, v61, vcc
	v_cmp_ngt_f32_e64 vcc, |v46|, s50
	s_nop 1
	v_cndmask_b32_e32 v46, v227, v47, vcc
	v_add_f32_e32 v47, 0xc1b80000, v63
	v_fma_f32 v185, -v186, |v47|, -v188
	v_cmp_ngt_f32_e64 vcc, |v47|, s50
	v_add_f32_e32 v63, 0xc25c0000, v63
	s_nop 0
	v_cndmask_b32_e32 v47, v227, v185, vcc
	v_fma_f32 v185, -v186, |v62|, -v188
	v_cmp_ngt_f32_e64 vcc, |v62|, s50
	s_waitcnt lgkmcnt(1)
	v_mfma_f32_32x32x16_bf16 v[32:47], v[200:203], v[136:139], v[32:47]
	v_cndmask_b32_e32 v62, v227, v185, vcc
	v_fma_f32 v185, -v186, |v63|, -v188
	v_cmp_ngt_f32_e64 vcc, |v63|, s50
	s_nop 1
	v_cndmask_b32_e32 v63, v227, v185, vcc
	s_waitcnt lgkmcnt(0)
	s_nop 0
	v_mfma_f32_32x32x16_bf16 v[48:63], v[204:207], v[136:139], v[48:63]
	ds_read_b128 v[200:203], v224
	ds_read_b128 v[204:207], v224 offset:4096
	s_waitcnt lgkmcnt(1)
	v_mfma_f32_32x32x16_bf16 v[32:47], v[200:203], v[132:135], v[32:47]
	s_waitcnt lgkmcnt(0)
	v_mfma_f32_32x32x16_bf16 v[48:63], v[204:207], v[132:135], v[48:63]
	ds_read_b128 v[200:203], v225
	ds_read_b128 v[204:207], v225 offset:4096
	s_waitcnt lgkmcnt(1)
	v_mfma_f32_32x32x16_bf16 v[32:47], v[200:203], v[128:131], v[32:47]
	s_waitcnt lgkmcnt(0)
	v_mfma_f32_32x32x16_bf16 v[48:63], v[204:207], v[128:131], v[48:63]
	ds_read_b128 v[200:203], v226
	ds_read_b128 v[204:207], v226 offset:4096
	s_waitcnt lgkmcnt(1)
	v_mfma_f32_32x32x16_bf16 v[32:47], v[200:203], v[124:127], v[32:47]
	s_waitcnt lgkmcnt(0)
	v_mfma_f32_32x32x16_bf16 v[48:63], v[204:207], v[124:127], v[48:63]
	s_nop 9
	v_max_f32_e32 v185, v33, v49
	v_max_f32_e32 v200, v34, v50
	v_max3_f32 v185, v32, v48, v185
	v_max_f32_e32 v201, v35, v51
	v_max3_f32 v185, v185, v200, v201
	v_max_f32_e32 v200, v36, v52
	v_max_f32_e32 v201, v37, v53
	v_max3_f32 v185, v185, v200, v201
	v_max_f32_e32 v200, v38, v54
	v_max_f32_e32 v201, v39, v55
	v_max3_f32 v185, v185, v200, v201
	v_max_f32_e32 v200, v40, v56
	v_max_f32_e32 v201, v41, v57
	v_max3_f32 v185, v185, v200, v201
	v_max_f32_e32 v200, v42, v58
	v_max_f32_e32 v201, v43, v59
	v_max3_f32 v185, v185, v200, v201
	v_max_f32_e32 v200, v44, v60
	v_max_f32_e32 v201, v45, v61
	v_max3_f32 v185, v185, v200, v201
	v_max_f32_e32 v200, v46, v62
	v_max_f32_e32 v201, v47, v63
	v_max3_f32 v185, v185, v200, v201
	v_mov_b32_e32 v200, v185
	s_nop 1
	v_permlane32_swap_b32 v185, v200
	s_nop 1
	s_nop 0
	v_max_f32_e32 v200, v200, v200
	v_max_f32_e32 v185, v185, v185
	v_max_f32_e32 v185, v185, v200
	v_cmp_lt_f32_e32 vcc, s51, v185
	s_cbranch_vccz .LBB0_516
	v_max_f32_e32 v185, v185, v185
	v_max_f32_e32 v200, 0, v185
	v_exp_f32_e64 v202, -v200
	v_add_f32_e32 v188, v188, v200
	v_pk_add_f32 v[32:33], v[32:33], v[200:201] op_sel_hi:[1,0] neg_lo:[0,1] neg_hi:[0,1]
	v_pk_add_f32 v[48:49], v[48:49], v[200:201] op_sel_hi:[1,0] neg_lo:[0,1] neg_hi:[0,1]
	v_pk_add_f32 v[34:35], v[34:35], v[200:201] op_sel_hi:[1,0] neg_lo:[0,1] neg_hi:[0,1]
	v_pk_add_f32 v[50:51], v[50:51], v[200:201] op_sel_hi:[1,0] neg_lo:[0,1] neg_hi:[0,1]
	v_pk_add_f32 v[36:37], v[36:37], v[200:201] op_sel_hi:[1,0] neg_lo:[0,1] neg_hi:[0,1]
	v_pk_add_f32 v[52:53], v[52:53], v[200:201] op_sel_hi:[1,0] neg_lo:[0,1] neg_hi:[0,1]
	v_pk_add_f32 v[38:39], v[38:39], v[200:201] op_sel_hi:[1,0] neg_lo:[0,1] neg_hi:[0,1]
	v_pk_add_f32 v[54:55], v[54:55], v[200:201] op_sel_hi:[1,0] neg_lo:[0,1] neg_hi:[0,1]
	v_pk_add_f32 v[40:41], v[40:41], v[200:201] op_sel_hi:[1,0] neg_lo:[0,1] neg_hi:[0,1]
	v_pk_add_f32 v[56:57], v[56:57], v[200:201] op_sel_hi:[1,0] neg_lo:[0,1] neg_hi:[0,1]
	v_pk_add_f32 v[42:43], v[42:43], v[200:201] op_sel_hi:[1,0] neg_lo:[0,1] neg_hi:[0,1]
	v_pk_add_f32 v[58:59], v[58:59], v[200:201] op_sel_hi:[1,0] neg_lo:[0,1] neg_hi:[0,1]
	v_pk_add_f32 v[44:45], v[44:45], v[200:201] op_sel_hi:[1,0] neg_lo:[0,1] neg_hi:[0,1]
	v_pk_add_f32 v[60:61], v[60:61], v[200:201] op_sel_hi:[1,0] neg_lo:[0,1] neg_hi:[0,1]
	v_pk_add_f32 v[46:47], v[46:47], v[200:201] op_sel_hi:[1,0] neg_lo:[0,1] neg_hi:[0,1]
	v_pk_add_f32 v[62:63], v[62:63], v[200:201] op_sel_hi:[1,0] neg_lo:[0,1] neg_hi:[0,1]
	v_mul_f32_e32 v189, v189, v202
	v_pk_mul_f32 v[30:31], v[30:31], v[202:203] op_sel_hi:[1,0]
	v_pk_mul_f32 v[28:29], v[28:29], v[202:203] op_sel_hi:[1,0]
	v_pk_mul_f32 v[26:27], v[26:27], v[202:203] op_sel_hi:[1,0]
	v_pk_mul_f32 v[24:25], v[24:25], v[202:203] op_sel_hi:[1,0]
	v_pk_mul_f32 v[22:23], v[22:23], v[202:203] op_sel_hi:[1,0]
	v_pk_mul_f32 v[20:21], v[20:21], v[202:203] op_sel_hi:[1,0]
	v_pk_mul_f32 v[18:19], v[18:19], v[202:203] op_sel_hi:[1,0]
	v_pk_mul_f32 v[16:17], v[16:17], v[202:203] op_sel_hi:[1,0]
	v_pk_mul_f32 v[14:15], v[14:15], v[202:203] op_sel_hi:[1,0]
	v_pk_mul_f32 v[12:13], v[12:13], v[202:203] op_sel_hi:[1,0]
	v_pk_mul_f32 v[10:11], v[10:11], v[202:203] op_sel_hi:[1,0]
	v_pk_mul_f32 v[8:9], v[8:9], v[202:203] op_sel_hi:[1,0]
	v_pk_mul_f32 v[6:7], v[6:7], v[202:203] op_sel_hi:[1,0]
	v_pk_mul_f32 v[4:5], v[4:5], v[202:203] op_sel_hi:[1,0]
	v_pk_mul_f32 v[2:3], v[2:3], v[202:203] op_sel_hi:[1,0]
	v_pk_mul_f32 v[0:1], v[0:1], v[202:203] op_sel_hi:[1,0]

.LBB0_519:
	v_subrev_u32_e32 v32, s84, v228
	v_cvt_f32_i32_e32 v47, v32
	ds_read_b128 v[200:203], v223
	ds_read_b128 v[204:207], v223 offset:4096
	v_add_f32_e32 v33, 0xc2000000, v47
	v_fma_f32 v32, -v186, |v47|, -v188
	v_cmp_ngt_f32_e64 vcc, |v47|, s50
	v_fma_f32 v34, -v186, |v33|, -v188
	s_nop 0
	v_cndmask_b32_e32 v32, v227, v32, vcc
	v_cmp_ngt_f32_e64 vcc, |v33|, s50
	v_add_f32_e32 v33, -1.0, v47
	v_fma_f32 v35, -v186, |v33|, -v188
	v_cndmask_b32_e32 v48, v227, v34, vcc
	v_add_f32_e32 v34, 0xc2040000, v47
	v_cmp_ngt_f32_e64 vcc, |v33|, s50
	v_fma_f32 v36, -v186, |v34|, -v188
	s_nop 0
	v_cndmask_b32_e32 v33, v227, v35, vcc
	v_cmp_ngt_f32_e64 vcc, |v34|, s50
	v_add_f32_e32 v34, -2.0, v47
	v_add_f32_e32 v35, 0xc2080000, v47
	v_cndmask_b32_e32 v49, v227, v36, vcc
	v_fma_f32 v36, -v186, |v34|, -v188
	v_cmp_ngt_f32_e64 vcc, |v34|, s50
	v_fma_f32 v37, -v186, |v35|, -v188
	s_nop 0
	v_cndmask_b32_e32 v34, v227, v36, vcc
	v_cmp_ngt_f32_e64 vcc, |v35|, s50
	v_add_f32_e32 v35, 0xc0400000, v47
	v_add_f32_e32 v36, 0xc20c0000, v47
	v_cndmask_b32_e32 v50, v227, v37, vcc
	v_fma_f32 v37, -v186, |v35|, -v188
	v_cmp_ngt_f32_e64 vcc, |v35|, s50
	v_fma_f32 v38, -v186, |v36|, -v188
	s_nop 0
	v_cndmask_b32_e32 v35, v227, v37, vcc
	v_cmp_ngt_f32_e64 vcc, |v36|, s50
	v_add_f32_e32 v36, -4.0, v47
	v_add_f32_e32 v37, 0xc2100000, v47
	v_cndmask_b32_e32 v51, v227, v38, vcc
	v_fma_f32 v38, -v186, |v36|, -v188
	v_cmp_ngt_f32_e64 vcc, |v36|, s50
	v_fma_f32 v39, -v186, |v37|, -v188
	s_nop 0
	v_cndmask_b32_e32 v36, v227, v38, vcc
	v_cmp_ngt_f32_e64 vcc, |v37|, s50
	v_add_f32_e32 v37, 0xc0a00000, v47
	v_add_f32_e32 v38, 0xc2140000, v47
	v_cndmask_b32_e32 v52, v227, v39, vcc
	v_fma_f32 v39, -v186, |v37|, -v188
	v_cmp_ngt_f32_e64 vcc, |v37|, s50
	v_fma_f32 v40, -v186, |v38|, -v188
	s_nop 0
	v_cndmask_b32_e32 v37, v227, v39, vcc
	v_cmp_ngt_f32_e64 vcc, |v38|, s50
	v_add_f32_e32 v38, 0xc0c00000, v47
	v_add_f32_e32 v39, 0xc2180000, v47
	v_cndmask_b32_e32 v53, v227, v40, vcc
	v_fma_f32 v40, -v186, |v38|, -v188
	v_cmp_ngt_f32_e64 vcc, |v38|, s50
	v_fma_f32 v41, -v186, |v39|, -v188
	s_nop 0
	v_cndmask_b32_e32 v38, v227, v40, vcc
	v_cmp_ngt_f32_e64 vcc, |v39|, s50
	v_add_f32_e32 v39, 0xc0e00000, v47
	v_add_f32_e32 v40, 0xc21c0000, v47
	v_cndmask_b32_e32 v54, v227, v41, vcc
	v_fma_f32 v41, -v186, |v39|, -v188
	v_cmp_ngt_f32_e64 vcc, |v39|, s50
	v_fma_f32 v42, -v186, |v40|, -v188
	s_nop 0
	v_cndmask_b32_e32 v39, v227, v41, vcc
	v_cmp_ngt_f32_e64 vcc, |v40|, s50
	v_add_f32_e32 v40, 0xc1800000, v47
	v_add_f32_e32 v41, 0xc2400000, v47
	v_cndmask_b32_e32 v55, v227, v42, vcc
	v_fma_f32 v42, -v186, |v40|, -v188
	v_cmp_ngt_f32_e64 vcc, |v40|, s50
	v_fma_f32 v43, -v186, |v41|, -v188
	s_nop 0
	v_cndmask_b32_e32 v40, v227, v42, vcc
	v_cmp_ngt_f32_e64 vcc, |v41|, s50
	v_add_f32_e32 v41, 0xc1880000, v47
	v_add_f32_e32 v42, 0xc2440000, v47
	v_cndmask_b32_e32 v56, v227, v43, vcc
	v_fma_f32 v43, -v186, |v41|, -v188
	v_cmp_ngt_f32_e64 vcc, |v41|, s50
	v_fma_f32 v44, -v186, |v42|, -v188
	s_nop 0
	v_cndmask_b32_e32 v41, v227, v43, vcc
	v_cmp_ngt_f32_e64 vcc, |v42|, s50
	v_add_f32_e32 v42, 0xc1900000, v47
	v_add_f32_e32 v43, 0xc2480000, v47
	v_cndmask_b32_e32 v57, v227, v44, vcc
	v_fma_f32 v44, -v186, |v42|, -v188
	v_cmp_ngt_f32_e64 vcc, |v42|, s50
	v_fma_f32 v45, -v186, |v43|, -v188
	s_nop 0
	v_cndmask_b32_e32 v42, v227, v44, vcc
	v_cmp_ngt_f32_e64 vcc, |v43|, s50
	v_add_f32_e32 v43, 0xc1980000, v47
	v_add_f32_e32 v44, 0xc24c0000, v47
	v_cndmask_b32_e32 v58, v227, v45, vcc
	v_fma_f32 v45, -v186, |v43|, -v188
	v_cmp_ngt_f32_e64 vcc, |v43|, s50
	v_fma_f32 v46, -v186, |v44|, -v188
	s_nop 0
	v_cndmask_b32_e32 v43, v227, v45, vcc
	v_cmp_ngt_f32_e64 vcc, |v44|, s50
	v_add_f32_e32 v44, 0xc1a00000, v47
	v_add_f32_e32 v45, 0xc2500000, v47
	v_cndmask_b32_e32 v59, v227, v46, vcc
	v_fma_f32 v46, -v186, |v44|, -v188
	v_cmp_ngt_f32_e64 vcc, |v44|, s50
	v_fma_f32 v60, -v186, |v45|, -v188
	s_nop 0
	v_cndmask_b32_e32 v44, v227, v46, vcc
	v_cmp_ngt_f32_e64 vcc, |v45|, s50
	v_add_f32_e32 v45, 0xc1a80000, v47
	v_add_f32_e32 v46, 0xc2540000, v47
	v_cndmask_b32_e32 v60, v227, v60, vcc
	v_fma_f32 v61, -v186, |v45|, -v188
	v_cmp_ngt_f32_e64 vcc, |v45|, s50
	v_fma_f32 v62, -v186, |v46|, -v188
	s_nop 0
	v_cndmask_b32_e32 v45, v227, v61, vcc
	v_cmp_ngt_f32_e64 vcc, |v46|, s50
	v_add_f32_e32 v46, 0xc1b00000, v47
	v_fma_f32 v63, -v186, |v46|, -v188
	v_cndmask_b32_e32 v61, v227, v62, vcc
	v_add_f32_e32 v62, 0xc2580000, v47
	v_cmp_ngt_f32_e64 vcc, |v46|, s50
	v_fma_f32 v185, -v186, |v62|, -v188
	s_nop 0
	v_cndmask_b32_e32 v46, v227, v63, vcc
	v_cmp_ngt_f32_e64 vcc, |v62|, s50
	v_add_f32_e32 v63, 0xc1b80000, v47
	s_nop 0
	v_cndmask_b32_e32 v62, v227, v185, vcc
	v_add_f32_e32 v185, 0xc25c0000, v47
	v_fma_f32 v47, -v186, |v63|, -v188
	v_cmp_ngt_f32_e64 vcc, |v63|, s50
	v_fma_f32 v186, -v186, |v185|, -v188
	s_nop 0
	v_cndmask_b32_e32 v47, v227, v47, vcc
	v_cmp_ngt_f32_e64 vcc, |v185|, s50
	s_waitcnt lgkmcnt(1)
	v_mfma_f32_32x32x16_bf16 v[32:47], v[200:203], v[136:139], v[32:47]
	v_cndmask_b32_e32 v63, v227, v186, vcc
	s_waitcnt lgkmcnt(0)
	s_nop 0
	v_mfma_f32_32x32x16_bf16 v[48:63], v[204:207], v[136:139], v[48:63]
	ds_read_b128 v[136:139], v224
	ds_read_b128 v[200:203], v224 offset:4096
	s_waitcnt lgkmcnt(1)
	v_mfma_f32_32x32x16_bf16 v[32:47], v[136:139], v[132:135], v[32:47]
	s_waitcnt lgkmcnt(0)
	v_mfma_f32_32x32x16_bf16 v[48:63], v[200:203], v[132:135], v[48:63]
	ds_read_b128 v[132:135], v225
	ds_read_b128 v[136:139], v225 offset:4096
	s_waitcnt lgkmcnt(1)
	v_mfma_f32_32x32x16_bf16 v[32:47], v[132:135], v[128:131], v[32:47]
	s_waitcnt lgkmcnt(0)
	v_mfma_f32_32x32x16_bf16 v[48:63], v[136:139], v[128:131], v[48:63]
	ds_read_b128 v[128:131], v226
	ds_read_b128 v[132:135], v226 offset:4096
	s_waitcnt lgkmcnt(1)
	v_mfma_f32_32x32x16_bf16 v[32:47], v[128:131], v[124:127], v[32:47]
	s_waitcnt lgkmcnt(0)
	v_mfma_f32_32x32x16_bf16 v[48:63], v[132:135], v[124:127], v[48:63]
	s_nop 9
	v_max_f32_e32 v124, v33, v49
	v_max_f32_e32 v125, v34, v50
	v_max3_f32 v124, v32, v48, v124
	v_max_f32_e32 v126, v35, v51
	v_max3_f32 v124, v124, v125, v126
	v_max_f32_e32 v125, v36, v52
	v_max_f32_e32 v126, v37, v53
	v_max3_f32 v124, v124, v125, v126
	v_max_f32_e32 v125, v38, v54
	v_max_f32_e32 v126, v39, v55
	v_max3_f32 v124, v124, v125, v126
	v_max_f32_e32 v125, v40, v56
	v_max_f32_e32 v126, v41, v57
	v_max3_f32 v124, v124, v125, v126
	v_max_f32_e32 v125, v42, v58
	v_max_f32_e32 v126, v43, v59
	v_max3_f32 v124, v124, v125, v126
	v_max_f32_e32 v125, v44, v60
	v_max_f32_e32 v126, v45, v61
	v_max3_f32 v124, v124, v125, v126
	v_max_f32_e32 v125, v46, v62
	v_max_f32_e32 v126, v47, v63
	v_max3_f32 v124, v124, v125, v126
	v_mov_b32_e32 v125, v124
	s_nop 1
	v_permlane32_swap_b32 v125, v124
	s_nop 1
	s_nop 0
	v_max_f32_e32 v124, v124, v124
	v_max_f32_e32 v125, v125, v125
	v_max_f32_e32 v124, v125, v124
	v_cmp_lt_f32_e32 vcc, s51, v124
	s_cbranch_vccz .LBB0_521
	v_max_f32_e32 v124, v124, v124
	v_max_f32_e32 v124, 0, v124
	v_exp_f32_e64 v126, -v124
	v_add_f32_e32 v188, v188, v124
	v_pk_add_f32 v[32:33], v[32:33], v[124:125] op_sel_hi:[1,0] neg_lo:[0,1] neg_hi:[0,1]
	v_pk_add_f32 v[48:49], v[48:49], v[124:125] op_sel_hi:[1,0] neg_lo:[0,1] neg_hi:[0,1]
	v_pk_add_f32 v[34:35], v[34:35], v[124:125] op_sel_hi:[1,0] neg_lo:[0,1] neg_hi:[0,1]
	v_pk_add_f32 v[50:51], v[50:51], v[124:125] op_sel_hi:[1,0] neg_lo:[0,1] neg_hi:[0,1]
	v_pk_add_f32 v[36:37], v[36:37], v[124:125] op_sel_hi:[1,0] neg_lo:[0,1] neg_hi:[0,1]
	v_pk_add_f32 v[52:53], v[52:53], v[124:125] op_sel_hi:[1,0] neg_lo:[0,1] neg_hi:[0,1]
	v_pk_add_f32 v[38:39], v[38:39], v[124:125] op_sel_hi:[1,0] neg_lo:[0,1] neg_hi:[0,1]
	v_pk_add_f32 v[54:55], v[54:55], v[124:125] op_sel_hi:[1,0] neg_lo:[0,1] neg_hi:[0,1]
	v_pk_add_f32 v[40:41], v[40:41], v[124:125] op_sel_hi:[1,0] neg_lo:[0,1] neg_hi:[0,1]
	v_pk_add_f32 v[56:57], v[56:57], v[124:125] op_sel_hi:[1,0] neg_lo:[0,1] neg_hi:[0,1]
	v_pk_add_f32 v[42:43], v[42:43], v[124:125] op_sel_hi:[1,0] neg_lo:[0,1] neg_hi:[0,1]
	v_pk_add_f32 v[58:59], v[58:59], v[124:125] op_sel_hi:[1,0] neg_lo:[0,1] neg_hi:[0,1]
	v_pk_add_f32 v[44:45], v[44:45], v[124:125] op_sel_hi:[1,0] neg_lo:[0,1] neg_hi:[0,1]
	v_pk_add_f32 v[60:61], v[60:61], v[124:125] op_sel_hi:[1,0] neg_lo:[0,1] neg_hi:[0,1]
	v_pk_add_f32 v[46:47], v[46:47], v[124:125] op_sel_hi:[1,0] neg_lo:[0,1] neg_hi:[0,1]
	v_pk_add_f32 v[62:63], v[62:63], v[124:125] op_sel_hi:[1,0] neg_lo:[0,1] neg_hi:[0,1]
	v_mul_f32_e32 v189, v189, v126
	v_pk_mul_f32 v[30:31], v[30:31], v[126:127] op_sel_hi:[1,0]
	v_pk_mul_f32 v[28:29], v[28:29], v[126:127] op_sel_hi:[1,0]
	v_pk_mul_f32 v[26:27], v[26:27], v[126:127] op_sel_hi:[1,0]
	v_pk_mul_f32 v[24:25], v[24:25], v[126:127] op_sel_hi:[1,0]
	v_pk_mul_f32 v[22:23], v[22:23], v[126:127] op_sel_hi:[1,0]
	v_pk_mul_f32 v[20:21], v[20:21], v[126:127] op_sel_hi:[1,0]
	v_pk_mul_f32 v[18:19], v[18:19], v[126:127] op_sel_hi:[1,0]
	v_pk_mul_f32 v[16:17], v[16:17], v[126:127] op_sel_hi:[1,0]
	v_pk_mul_f32 v[14:15], v[14:15], v[126:127] op_sel_hi:[1,0]
	v_pk_mul_f32 v[12:13], v[12:13], v[126:127] op_sel_hi:[1,0]
	v_pk_mul_f32 v[10:11], v[10:11], v[126:127] op_sel_hi:[1,0]
	v_pk_mul_f32 v[8:9], v[8:9], v[126:127] op_sel_hi:[1,0]
	v_pk_mul_f32 v[6:7], v[6:7], v[126:127] op_sel_hi:[1,0]
	v_pk_mul_f32 v[4:5], v[4:5], v[126:127] op_sel_hi:[1,0]
	v_pk_mul_f32 v[2:3], v[2:3], v[126:127] op_sel_hi:[1,0]
	v_pk_mul_f32 v[0:1], v[0:1], v[126:127] op_sel_hi:[1,0]
